# FFN-up K-loop: priority 1 for the load section (LDS reads + LDS-DMA issue), 0 for the MFMA block
# speedup vs baseline: 1.0256x; 1.0256x over previous
; #define PG8_STAGE(bufoff, gbase, voff) do { _Pragma("unroll") for (int _i = 0; _i < 2; ++_i) \
;         __builtin_amdgcn_global_load_lds((const unsigned*)((const char*)(gbase) + (voff)[_i]), (LAS unsigned*)(lds + (bufoff) + ldsw + _i * 8192), 16, 0, 0); } while (0)
; #define PG8_LDA(dst, b, h) do { _Pragma("unroll") for (int m = 0; m < 4; ++m) _Pragma("unroll") for (int k = 0; k < 2; ++k) dst[m][k] = *(const LAS bf16x8*)(lds + PG8_SA(b, h) + aoff + m * 2048 + k * 1024); } while (0)
; #define PG8_LDB(dst, b, h) do { _Pragma("unroll") for (int n = 0; n < 2; ++n) _Pragma("unroll") for (int k = 0; k < 2; ++k) dst[n][k] = *(const LAS bf16x8*)(lds + PG8_SB(b, h) + boff + n * 2048 + k * 1024); } while (0)
; #define PG8_MMA(ai, bj, At, Bt) do { __builtin_amdgcn_s_setprio(1); _Pragma("unroll") for (int m = 0; m < 4; ++m) _Pragma("unroll") for (int n = 0; n < 2; ++n) _Pragma("unroll") for (int k = 0; k < 2; ++k) \
;         acc[ai][bj][m][n] = __builtin_amdgcn_mfma_f32_16x16x32_bf16(Bt[n][k], At[m][k], acc[ai][bj][m][n], 0, 0, 0); __builtin_amdgcn_s_setprio(0); } while (0)
; #define PG8_WAIT_V(n) asm volatile("s_waitcnt vmcnt(" #n ")" ::: "memory")
; #define PG8_WAIT_L(n) asm volatile("s_waitcnt lgkmcnt(" #n ")" ::: "memory")
; #define PG8_BAR __builtin_amdgcn_s_barrier()
; #define PG8_SCHED __builtin_amdgcn_sched_barrier(0)
; template <class Epi, class Sched>
; __device__ __forceinline__ void gemm_phase(LAS unsigned char* lds, const int K, const Sched& S, const Epi& E) {
;     ...
;             PG8_LDB(B0, 0, 0); PG8_SCHED; PG8_LDA(At, 0, 0); PG8_STAGE(PG8_SA(1, 1), a1 + hstepA, voffA);
;             PG8_WAIT_L(8); PG8_BAR; PG8_WAIT_L(0); PG8_MMA(0, 0, At, B0); PG8_BAR; PG8_SCHED;
;             PG8_LDB(B1, 0, 1); PG8_STAGE(PG8_SB(0, 0), b2, voffB);
;             PG8_BAR; PG8_WAIT_L(0); PG8_MMA(0, 1, At, B1); PG8_BAR;
;             PG8_LDA(At, 0, 1); PG8_STAGE(PG8_SA(0, 0), a2, voffA);
;             PG8_BAR; PG8_WAIT_L(0); PG8_MMA(1, 0, At, B0); PG8_BAR; PG8_SCHED;
;             PG8_STAGE(PG8_SB(0, 1), b2 + hstep, voffB);
;             PG8_WAIT_V(6); PG8_BAR; PG8_MMA(1, 1, At, B1); PG8_BAR;
.Lpeel_p7:
	ds_read_b128 v[128:131], v158
	ds_read_b128 v[132:135], v158 offset:1024
	ds_read_b128 v[148:151], v158 offset:2048
	ds_read_b128 v[162:165], v158 offset:3072
	s_add_u32 s68, s12, 0x100
	s_addc_u32 s69, s13, 0
	s_cmp_eq_u32 s49, 12
	s_cselect_b32 s73, s63, s69
	s_cselect_b32 s72, s62, s68
	s_cselect_b32 s71, s65, s33
	s_cselect_b32 s70, s64, s11
	v_lshl_add_u64 v[200:201], s[12:13], 0, v[144:145]
	s_add_i32 m0, s67, 0xc000
	ds_read_b128 v[166:169], v159
	ds_read_b128 v[172:175], v159 offset:1024
	ds_read_b128 v[176:179], v159 offset:2048
	ds_read_b128 v[180:183], v159 offset:3072
	ds_read_b128 v[184:187], v159 offset:4096
	ds_read_b128 v[188:191], v159 offset:5120
	ds_read_b128 v[192:195], v159 offset:6144
	ds_read_b128 v[196:199], v159 offset:7168
	global_load_lds_dwordx4 v[200:201], off
	v_lshl_add_u64 v[200:201], s[12:13], 0, v[146:147]
	s_add_i32 m0, s67, 0xe000
	s_nop 0
	global_load_lds_dwordx4 v[200:201], off
	s_waitcnt lgkmcnt(8)
	s_barrier
	s_waitcnt lgkmcnt(0)
	s_setprio 0
	s_waitcnt lgkmcnt(0)
	v_mfma_f32_16x16x32_bf16 v[84:87], v[128:131], v[166:169], 0
	v_mfma_f32_16x16x32_bf16 v[76:79], v[148:151], v[166:169], 0
	v_mfma_f32_16x16x32_bf16 v[124:127], v[128:131], v[176:179], 0
	v_mfma_f32_16x16x32_bf16 v[72:75], v[148:151], v[176:179], 0
	v_mfma_f32_16x16x32_bf16 v[120:123], v[128:131], v[184:187], 0
	v_mfma_f32_16x16x32_bf16 v[96:99], v[148:151], v[184:187], 0
	v_mfma_f32_16x16x32_bf16 v[116:119], v[128:131], v[192:195], 0
	v_mfma_f32_16x16x32_bf16 v[92:95], v[148:151], v[192:195], 0
	v_mfma_f32_16x16x32_bf16 v[84:87], v[132:135], v[172:175], v[84:87]
	v_mfma_f32_16x16x32_bf16 v[76:79], v[162:165], v[172:175], v[76:79]
	v_mfma_f32_16x16x32_bf16 v[124:127], v[132:135], v[180:183], v[124:127]
	v_mfma_f32_16x16x32_bf16 v[72:75], v[162:165], v[180:183], v[72:75]
	v_mfma_f32_16x16x32_bf16 v[120:123], v[132:135], v[188:191], v[120:123]
	v_mfma_f32_16x16x32_bf16 v[96:99], v[162:165], v[188:191], v[96:99]
	v_mfma_f32_16x16x32_bf16 v[116:119], v[132:135], v[196:199], v[116:119]
	v_mfma_f32_16x16x32_bf16 v[92:95], v[162:165], v[196:199], v[92:95]
	s_setprio 1
	s_barrier
	s_add_i32 s12, s88, s78
	v_lshl_add_u64 v[216:217], s[70:71], 0, v[138:139]
	s_mov_b32 m0, s12
	ds_read_b128 v[200:203], v160
	ds_read_b128 v[204:207], v160 offset:1024
	ds_read_b128 v[208:211], v160 offset:2048
	ds_read_b128 v[212:215], v160 offset:3072
	global_load_lds_dwordx4 v[216:217], off
	v_lshl_add_u64 v[218:219], s[70:71], 0, v[142:143]
	s_add_i32 m0, s12, 0x2000
	s_nop 0
	global_load_lds_dwordx4 v[218:219], off
	s_barrier
	s_waitcnt lgkmcnt(0)
	s_setprio 0
	s_waitcnt lgkmcnt(0)
	v_mfma_f32_16x16x32_bf16 v[60:63], v[200:203], v[166:169], 0
	v_mfma_f32_16x16x32_bf16 v[16:19], v[208:211], v[166:169], 0
	v_mfma_f32_16x16x32_bf16 v[56:59], v[200:203], v[176:179], 0
	v_mfma_f32_16x16x32_bf16 v[12:15], v[208:211], v[176:179], 0
	v_mfma_f32_16x16x32_bf16 v[52:55], v[200:203], v[184:187], 0
	v_mfma_f32_16x16x32_bf16 v[28:31], v[208:211], v[184:187], 0
	v_mfma_f32_16x16x32_bf16 v[48:51], v[200:203], v[192:195], 0
	v_mfma_f32_16x16x32_bf16 v[24:27], v[208:211], v[192:195], 0
	v_mfma_f32_16x16x32_bf16 v[60:63], v[204:207], v[172:175], v[60:63]
	v_mfma_f32_16x16x32_bf16 v[16:19], v[212:215], v[172:175], v[16:19]
	v_mfma_f32_16x16x32_bf16 v[56:59], v[204:207], v[180:183], v[56:59]
	v_mfma_f32_16x16x32_bf16 v[12:15], v[212:215], v[180:183], v[12:15]
	v_mfma_f32_16x16x32_bf16 v[52:55], v[204:207], v[188:191], v[52:55]
	v_mfma_f32_16x16x32_bf16 v[28:31], v[212:215], v[188:191], v[28:31]
	v_mfma_f32_16x16x32_bf16 v[48:51], v[204:207], v[196:199], v[48:51]
	v_mfma_f32_16x16x32_bf16 v[24:27], v[212:215], v[196:199], v[24:27]
	s_setprio 1
	s_mov_b32 m0, s67
	v_lshl_add_u64 v[220:221], s[72:73], 0, v[136:137]
	s_barrier
	ds_read_b128 v[166:169], v159 offset:16384
	ds_read_b128 v[172:175], v159 offset:17408
	ds_read_b128 v[176:179], v159 offset:18432
	ds_read_b128 v[180:183], v159 offset:19456
	ds_read_b128 v[184:187], v159 offset:20480
	ds_read_b128 v[188:191], v159 offset:21504
	ds_read_b128 v[192:195], v159 offset:22528
	ds_read_b128 v[196:199], v159 offset:23552
	global_load_lds_dwordx4 v[220:221], off
	v_lshl_add_u64 v[222:223], s[72:73], 0, v[140:141]
	s_mov_b32 m0, s80
	s_nop 0
	global_load_lds_dwordx4 v[222:223], off
	s_barrier
	s_waitcnt lgkmcnt(0)
	s_setprio 0
	s_waitcnt lgkmcnt(0)
	v_mfma_f32_16x16x32_bf16 v[112:115], v[128:131], v[166:169], 0
	v_mfma_f32_16x16x32_bf16 v[88:91], v[148:151], v[166:169], 0
	v_mfma_f32_16x16x32_bf16 v[104:107], v[128:131], v[176:179], 0
	v_mfma_f32_16x16x32_bf16 v[80:83], v[148:151], v[176:179], 0
	v_mfma_f32_16x16x32_bf16 v[100:103], v[128:131], v[184:187], 0
	v_mfma_f32_16x16x32_bf16 v[64:67], v[148:151], v[184:187], 0
	v_mfma_f32_16x16x32_bf16 v[108:111], v[128:131], v[192:195], 0
	v_mfma_f32_16x16x32_bf16 v[68:71], v[148:151], v[192:195], 0
	v_mfma_f32_16x16x32_bf16 v[112:115], v[132:135], v[172:175], v[112:115]
	v_mfma_f32_16x16x32_bf16 v[88:91], v[162:165], v[172:175], v[88:91]
	v_mfma_f32_16x16x32_bf16 v[104:107], v[132:135], v[180:183], v[104:107]
	v_mfma_f32_16x16x32_bf16 v[80:83], v[162:165], v[180:183], v[80:83]
	v_mfma_f32_16x16x32_bf16 v[100:103], v[132:135], v[188:191], v[100:103]
	v_mfma_f32_16x16x32_bf16 v[64:67], v[162:165], v[188:191], v[64:67]
	v_mfma_f32_16x16x32_bf16 v[108:111], v[132:135], v[196:199], v[108:111]
	v_mfma_f32_16x16x32_bf16 v[68:71], v[162:165], v[196:199], v[68:71]
	s_setprio 1
	s_barrier
	s_add_u32 s12, s70, 0x40000
	s_addc_u32 s13, s71, 0
	s_add_i32 s52, s89, s78
	v_lshl_add_u64 v[128:129], s[12:13], 0, v[138:139]
	s_mov_b32 m0, s52
	s_nop 0
	global_load_lds_dwordx4 v[128:129], off
	v_lshl_add_u64 v[128:129], s[12:13], 0, v[142:143]
	s_add_i32 m0, s52, 0x2000
	s_nop 0
	global_load_lds_dwordx4 v[128:129], off
	s_waitcnt vmcnt(6)
	s_barrier
; #define PG8_STAGE(bufoff, gbase, voff) do { _Pragma("unroll") for (int _i = 0; _i < 2; ++_i) \
;         __builtin_amdgcn_global_load_lds((const unsigned*)((const char*)(gbase) + (voff)[_i]), (LAS unsigned*)(lds + (bufoff) + ldsw + _i * 8192), 16, 0, 0); } while (0)
; #define PG8_LDA(dst, b, h) do { _Pragma("unroll") for (int m = 0; m < 4; ++m) _Pragma("unroll") for (int k = 0; k < 2; ++k) dst[m][k] = *(const LAS bf16x8*)(lds + PG8_SA(b, h) + aoff + m * 2048 + k * 1024); } while (0)
; #define PG8_LDB(dst, b, h) do { _Pragma("unroll") for (int n = 0; n < 2; ++n) _Pragma("unroll") for (int k = 0; k < 2; ++k) dst[n][k] = *(const LAS bf16x8*)(lds + PG8_SB(b, h) + boff + n * 2048 + k * 1024); } while (0)
; #define PG8_MMA(ai, bj, At, Bt) do { __builtin_amdgcn_s_setprio(1); _Pragma("unroll") for (int m = 0; m < 4; ++m) _Pragma("unroll") for (int n = 0; n < 2; ++n) _Pragma("unroll") for (int k = 0; k < 2; ++k) \
;         acc[ai][bj][m][n] = __builtin_amdgcn_mfma_f32_16x16x32_bf16(Bt[n][k], At[m][k], acc[ai][bj][m][n], 0, 0, 0); __builtin_amdgcn_s_setprio(0); } while (0)
; #define PG8_WAIT_V(n) asm volatile("s_waitcnt vmcnt(" #n ")" ::: "memory")
; #define PG8_WAIT_L(n) asm volatile("s_waitcnt lgkmcnt(" #n ")" ::: "memory")
; #define PG8_BAR __builtin_amdgcn_s_barrier()
; #define PG8_SCHED __builtin_amdgcn_sched_barrier(0)
; template <class Epi, class Sched>
; __device__ __forceinline__ void gemm_phase(LAS unsigned char* lds, const int K, const Sched& S, const Epi& E) {
;     ...
;             PG8_WAIT_V(6); PG8_BAR; PG8_MMA(1, 1, At, B1); PG8_BAR;
;             PG8_LDB(B0, 1, 0); PG8_SCHED; PG8_LDA(At, 1, 0); PG8_STAGE(PG8_SA(0, 1), a2 + hstepA, voffA);
;             PG8_WAIT_L(8); PG8_BAR; PG8_WAIT_L(0); PG8_MMA(0, 0, At, B0); PG8_BAR; PG8_SCHED;
;             PG8_LDB(B1, 1, 1); PG8_STAGE(PG8_SB(1, 0), b3, voffB);
;             PG8_BAR; PG8_WAIT_L(0); PG8_MMA(0, 1, At, B1); PG8_BAR;
;             PG8_LDA(At, 1, 1); PG8_STAGE(PG8_SA(1, 0), a3, voffA);
;             PG8_BAR; PG8_WAIT_L(0); PG8_MMA(1, 0, At, B0); PG8_BAR; PG8_SCHED;
	s_setprio 0
	v_mfma_f32_16x16x32_bf16 v[44:47], v[200:203], v[166:169], 0
	v_mfma_f32_16x16x32_bf16 v[20:23], v[208:211], v[166:169], 0
	v_mfma_f32_16x16x32_bf16 v[40:43], v[200:203], v[176:179], 0
	v_mfma_f32_16x16x32_bf16 v[8:11], v[208:211], v[176:179], 0
	v_mfma_f32_16x16x32_bf16 v[36:39], v[200:203], v[184:187], 0
	v_mfma_f32_16x16x32_bf16 v[0:3], v[208:211], v[184:187], 0
	v_mfma_f32_16x16x32_bf16 v[32:35], v[200:203], v[192:195], 0
	v_mfma_f32_16x16x32_bf16 v[4:7], v[208:211], v[192:195], 0
	v_mfma_f32_16x16x32_bf16 v[44:47], v[204:207], v[172:175], v[44:47]
	v_mfma_f32_16x16x32_bf16 v[20:23], v[212:215], v[172:175], v[20:23]
	v_mfma_f32_16x16x32_bf16 v[40:43], v[204:207], v[180:183], v[40:43]
	v_mfma_f32_16x16x32_bf16 v[8:11], v[212:215], v[180:183], v[8:11]
	v_mfma_f32_16x16x32_bf16 v[36:39], v[204:207], v[188:191], v[36:39]
	v_mfma_f32_16x16x32_bf16 v[0:3], v[212:215], v[188:191], v[0:3]
	v_mfma_f32_16x16x32_bf16 v[32:35], v[204:207], v[196:199], v[32:35]
	v_mfma_f32_16x16x32_bf16 v[4:7], v[212:215], v[196:199], v[4:7]
	s_setprio 1
	s_add_i32 s52, 0, 0x18000
	v_add_u32_e32 v161, s52, v156
	s_barrier
	ds_read_b128 v[128:131], v161
	ds_read_b128 v[132:135], v161 offset:1024
	ds_read_b128 v[148:151], v161 offset:2048
	ds_read_b128 v[162:165], v161 offset:3072
	s_add_u32 s12, s72, 0x20000
	s_addc_u32 s13, s73, 0
	s_mov_b32 m0, s81
	v_lshl_add_u64 v[200:201], s[12:13], 0, v[136:137]
	ds_read_b128 v[166:169], v159 offset:32768
	ds_read_b128 v[172:175], v159 offset:33792
	ds_read_b128 v[176:179], v159 offset:34816
	ds_read_b128 v[180:183], v159 offset:35840
	ds_read_b128 v[184:187], v159 offset:36864
	ds_read_b128 v[188:191], v159 offset:37888
	ds_read_b128 v[192:195], v159 offset:38912
	ds_read_b128 v[196:199], v159 offset:39936
	global_load_lds_dwordx4 v[200:201], off
	v_lshl_add_u64 v[200:201], s[12:13], 0, v[140:141]
	s_mov_b32 m0, s82
	s_nop 0
	global_load_lds_dwordx4 v[200:201], off
	s_waitcnt lgkmcnt(8)
	s_barrier
	s_waitcnt lgkmcnt(0)
	s_setprio 0
	s_waitcnt lgkmcnt(0)
	v_mfma_f32_16x16x32_bf16 v[84:87], v[128:131], v[166:169], v[84:87]
	v_mfma_f32_16x16x32_bf16 v[76:79], v[148:151], v[166:169], v[76:79]
	v_mfma_f32_16x16x32_bf16 v[124:127], v[128:131], v[176:179], v[124:127]
	v_mfma_f32_16x16x32_bf16 v[72:75], v[148:151], v[176:179], v[72:75]
	v_mfma_f32_16x16x32_bf16 v[120:123], v[128:131], v[184:187], v[120:123]
	v_mfma_f32_16x16x32_bf16 v[96:99], v[148:151], v[184:187], v[96:99]
	v_mfma_f32_16x16x32_bf16 v[116:119], v[128:131], v[192:195], v[116:119]
	v_mfma_f32_16x16x32_bf16 v[92:95], v[148:151], v[192:195], v[92:95]
	v_mfma_f32_16x16x32_bf16 v[84:87], v[132:135], v[172:175], v[84:87]
	v_mfma_f32_16x16x32_bf16 v[76:79], v[162:165], v[172:175], v[76:79]
	v_mfma_f32_16x16x32_bf16 v[124:127], v[132:135], v[180:183], v[124:127]
	v_mfma_f32_16x16x32_bf16 v[72:75], v[162:165], v[180:183], v[72:75]
	v_mfma_f32_16x16x32_bf16 v[120:123], v[132:135], v[188:191], v[120:123]
	v_mfma_f32_16x16x32_bf16 v[96:99], v[162:165], v[188:191], v[96:99]
	v_mfma_f32_16x16x32_bf16 v[116:119], v[132:135], v[196:199], v[116:119]
	v_mfma_f32_16x16x32_bf16 v[92:95], v[162:165], v[196:199], v[92:95]
	s_setprio 1
	s_barrier
	s_add_i32 s53, 0, 0x1c000
	s_add_i32 s12, s52, s78
	v_add_u32_e32 v161, s53, v156
	v_lshl_add_u64 v[216:217], v[216:217], 0, s[38:39]
	s_mov_b32 m0, s12
	ds_read_b128 v[200:203], v161
	ds_read_b128 v[204:207], v161 offset:1024
	ds_read_b128 v[208:211], v161 offset:2048
	ds_read_b128 v[212:215], v161 offset:3072
	global_load_lds_dwordx4 v[216:217], off
	v_lshl_add_u64 v[216:217], v[218:219], 0, s[38:39]
	s_add_i32 m0, s12, 0x2000
	s_nop 0
	global_load_lds_dwordx4 v[216:217], off
	s_barrier
	s_waitcnt lgkmcnt(0)
	s_setprio 0
	s_waitcnt lgkmcnt(0)
	v_mfma_f32_16x16x32_bf16 v[60:63], v[200:203], v[166:169], v[60:63]
	v_mfma_f32_16x16x32_bf16 v[16:19], v[208:211], v[166:169], v[16:19]
	v_mfma_f32_16x16x32_bf16 v[56:59], v[200:203], v[176:179], v[56:59]
	v_mfma_f32_16x16x32_bf16 v[12:15], v[208:211], v[176:179], v[12:15]
	v_mfma_f32_16x16x32_bf16 v[52:55], v[200:203], v[184:187], v[52:55]
	v_mfma_f32_16x16x32_bf16 v[28:31], v[208:211], v[184:187], v[28:31]
	v_mfma_f32_16x16x32_bf16 v[48:51], v[200:203], v[192:195], v[48:51]
	v_mfma_f32_16x16x32_bf16 v[24:27], v[208:211], v[192:195], v[24:27]
	v_mfma_f32_16x16x32_bf16 v[60:63], v[204:207], v[172:175], v[60:63]
	v_mfma_f32_16x16x32_bf16 v[16:19], v[212:215], v[172:175], v[16:19]
	v_mfma_f32_16x16x32_bf16 v[56:59], v[204:207], v[180:183], v[56:59]
	v_mfma_f32_16x16x32_bf16 v[12:15], v[212:215], v[180:183], v[12:15]
	v_mfma_f32_16x16x32_bf16 v[52:55], v[204:207], v[188:191], v[52:55]
	v_mfma_f32_16x16x32_bf16 v[28:31], v[212:215], v[188:191], v[28:31]
	v_mfma_f32_16x16x32_bf16 v[48:51], v[204:207], v[196:199], v[48:51]
	v_mfma_f32_16x16x32_bf16 v[24:27], v[212:215], v[196:199], v[24:27]
	s_setprio 1
	s_mov_b32 m0, s84
	v_lshl_add_u64 v[216:217], v[220:221], 0, s[38:39]
	s_barrier
	ds_read_b128 v[166:169], v159 offset:49152
	ds_read_b128 v[172:175], v159 offset:50176
	ds_read_b128 v[176:179], v159 offset:51200
	ds_read_b128 v[180:183], v159 offset:52224
	ds_read_b128 v[184:187], v159 offset:53248
	ds_read_b128 v[188:191], v159 offset:54272
	ds_read_b128 v[192:195], v159 offset:55296
	ds_read_b128 v[196:199], v159 offset:56320
	global_load_lds_dwordx4 v[216:217], off
	v_lshl_add_u64 v[216:217], v[222:223], 0, s[38:39]
	s_mov_b32 m0, s85
	s_nop 0
	global_load_lds_dwordx4 v[216:217], off
	s_barrier
; #define PG8_STAGE(bufoff, gbase, voff) do { _Pragma("unroll") for (int _i = 0; _i < 2; ++_i) \
;         __builtin_amdgcn_global_load_lds((const unsigned*)((const char*)(gbase) + (voff)[_i]), (LAS unsigned*)(lds + (bufoff) + ldsw + _i * 8192), 16, 0, 0); } while (0)
; #define PG8_LDA(dst, b, h) do { _Pragma("unroll") for (int m = 0; m < 4; ++m) _Pragma("unroll") for (int k = 0; k < 2; ++k) dst[m][k] = *(const LAS bf16x8*)(lds + PG8_SA(b, h) + aoff + m * 2048 + k * 1024); } while (0)
; #define PG8_LDB(dst, b, h) do { _Pragma("unroll") for (int n = 0; n < 2; ++n) _Pragma("unroll") for (int k = 0; k < 2; ++k) dst[n][k] = *(const LAS bf16x8*)(lds + PG8_SB(b, h) + boff + n * 2048 + k * 1024); } while (0)
; #define PG8_MMA(ai, bj, At, Bt) do { __builtin_amdgcn_s_setprio(1); _Pragma("unroll") for (int m = 0; m < 4; ++m) _Pragma("unroll") for (int n = 0; n < 2; ++n) _Pragma("unroll") for (int k = 0; k < 2; ++k) \
;         acc[ai][bj][m][n] = __builtin_amdgcn_mfma_f32_16x16x32_bf16(Bt[n][k], At[m][k], acc[ai][bj][m][n], 0, 0, 0); __builtin_amdgcn_s_setprio(0); } while (0)
; #define PG8_WAIT_V(n) asm volatile("s_waitcnt vmcnt(" #n ")" ::: "memory")
; #define PG8_WAIT_L(n) asm volatile("s_waitcnt lgkmcnt(" #n ")" ::: "memory")
; #define PG8_BAR __builtin_amdgcn_s_barrier()
; #define PG8_SCHED __builtin_amdgcn_sched_barrier(0)
; template <class Epi, class Sched>
; __device__ __forceinline__ void gemm_phase(LAS unsigned char* lds, const int K, const Sched& S, const Epi& E) {
;     ...
;             PG8_LDB(B0, 0, 0); PG8_SCHED; PG8_LDA(At, 0, 0); PG8_STAGE(PG8_SA(1, 1), a1 + hstepA, voffA);
;             PG8_WAIT_L(8); PG8_BAR; PG8_WAIT_L(0); PG8_MMA(0, 0, At, B0); PG8_BAR; PG8_SCHED;
;             PG8_LDB(B1, 0, 1); PG8_STAGE(PG8_SB(0, 0), b2, voffB);
;     ...
;             PG8_BAR; PG8_WAIT_L(0); PG8_MMA(1, 0, At, B0); PG8_BAR; PG8_SCHED;
;             PG8_STAGE(PG8_SB(1, 1), b3 + hstep, voffB);
;             PG8_WAIT_V(6); PG8_BAR; PG8_MMA(1, 1, At, B1); PG8_BAR;
	s_waitcnt lgkmcnt(0)
	s_setprio 0
	s_waitcnt lgkmcnt(0)
	v_mfma_f32_16x16x32_bf16 v[112:115], v[128:131], v[166:169], v[112:115]
	v_mfma_f32_16x16x32_bf16 v[88:91], v[148:151], v[166:169], v[88:91]
	v_mfma_f32_16x16x32_bf16 v[104:107], v[128:131], v[176:179], v[104:107]
	v_mfma_f32_16x16x32_bf16 v[80:83], v[148:151], v[176:179], v[80:83]
	v_mfma_f32_16x16x32_bf16 v[100:103], v[128:131], v[184:187], v[100:103]
	v_mfma_f32_16x16x32_bf16 v[64:67], v[148:151], v[184:187], v[64:67]
	v_mfma_f32_16x16x32_bf16 v[108:111], v[128:131], v[192:195], v[108:111]
	v_mfma_f32_16x16x32_bf16 v[68:71], v[148:151], v[192:195], v[68:71]
	v_mfma_f32_16x16x32_bf16 v[112:115], v[132:135], v[172:175], v[112:115]
	v_mfma_f32_16x16x32_bf16 v[88:91], v[162:165], v[172:175], v[88:91]
	v_mfma_f32_16x16x32_bf16 v[104:107], v[132:135], v[180:183], v[104:107]
	v_mfma_f32_16x16x32_bf16 v[80:83], v[162:165], v[180:183], v[80:83]
	v_mfma_f32_16x16x32_bf16 v[100:103], v[132:135], v[188:191], v[100:103]
	v_mfma_f32_16x16x32_bf16 v[64:67], v[162:165], v[188:191], v[64:67]
	v_mfma_f32_16x16x32_bf16 v[108:111], v[132:135], v[196:199], v[108:111]
	v_mfma_f32_16x16x32_bf16 v[68:71], v[162:165], v[196:199], v[68:71]
	s_setprio 1
	s_barrier
	s_add_u32 s12, s70, 0x40080
	s_addc_u32 s13, s71, 0
	s_add_i32 s52, s53, s78
	v_lshl_add_u64 v[128:129], s[12:13], 0, v[138:139]
	s_mov_b32 m0, s52
	s_nop 0
	global_load_lds_dwordx4 v[128:129], off
	v_lshl_add_u64 v[128:129], s[12:13], 0, v[142:143]
	s_add_i32 m0, s52, 0x2000
	s_nop 0
	global_load_lds_dwordx4 v[128:129], off
	s_waitcnt vmcnt(6)
	s_barrier
	s_setprio 0
	v_mfma_f32_16x16x32_bf16 v[44:47], v[200:203], v[166:169], v[44:47]
	v_mfma_f32_16x16x32_bf16 v[20:23], v[208:211], v[166:169], v[20:23]
	v_mfma_f32_16x16x32_bf16 v[40:43], v[200:203], v[176:179], v[40:43]
	v_mfma_f32_16x16x32_bf16 v[8:11], v[208:211], v[176:179], v[8:11]
	v_mfma_f32_16x16x32_bf16 v[36:39], v[200:203], v[184:187], v[36:39]
	v_mfma_f32_16x16x32_bf16 v[0:3], v[208:211], v[184:187], v[0:3]
	v_mfma_f32_16x16x32_bf16 v[32:35], v[200:203], v[192:195], v[32:35]
	v_mfma_f32_16x16x32_bf16 v[4:7], v[208:211], v[192:195], v[4:7]
	v_mfma_f32_16x16x32_bf16 v[44:47], v[204:207], v[172:175], v[44:47]
	v_mfma_f32_16x16x32_bf16 v[20:23], v[212:215], v[172:175], v[20:23]
	v_mfma_f32_16x16x32_bf16 v[40:43], v[204:207], v[180:183], v[40:43]
	v_mfma_f32_16x16x32_bf16 v[8:11], v[212:215], v[180:183], v[8:11]
	v_mfma_f32_16x16x32_bf16 v[36:39], v[204:207], v[188:191], v[36:39]
	v_mfma_f32_16x16x32_bf16 v[0:3], v[212:215], v[188:191], v[0:3]
	v_mfma_f32_16x16x32_bf16 v[32:35], v[204:207], v[196:199], v[32:35]
	v_mfma_f32_16x16x32_bf16 v[4:7], v[212:215], v[196:199], v[4:7]
	s_setprio 1
	s_add_i32 s49, s49, 2
	s_add_u32 s11, s11, 0x100
	s_addc_u32 s33, s33, 0
	s_cmp_gt_u32 s49, 13
	s_mov_b64 s[12:13], s[68:69]
	s_barrier
.LBB0_800:
	ds_read_b128 v[128:131], v158
	ds_read_b128 v[132:135], v158 offset:1024
	ds_read_b128 v[148:151], v158 offset:2048
	ds_read_b128 v[162:165], v158 offset:3072
	s_add_u32 s68, s12, 0x100
	s_addc_u32 s69, s13, 0
	s_cmp_eq_u32 s49, 12
	s_cselect_b32 s73, s63, s69
	s_cselect_b32 s72, s62, s68
	s_cselect_b32 s71, s65, s33
	s_cselect_b32 s70, s64, s11
	v_lshl_add_u64 v[200:201], s[12:13], 0, v[144:145]
	s_add_i32 m0, s67, 0xc000
	ds_read_b128 v[166:169], v159
	ds_read_b128 v[172:175], v159 offset:1024
	ds_read_b128 v[176:179], v159 offset:2048
	ds_read_b128 v[180:183], v159 offset:3072
	ds_read_b128 v[184:187], v159 offset:4096
	ds_read_b128 v[188:191], v159 offset:5120
	ds_read_b128 v[192:195], v159 offset:6144
	ds_read_b128 v[196:199], v159 offset:7168
	global_load_lds_dwordx4 v[200:201], off
	v_lshl_add_u64 v[200:201], s[12:13], 0, v[146:147]
	s_add_i32 m0, s67, 0xe000
	s_nop 0
	global_load_lds_dwordx4 v[200:201], off
	s_waitcnt lgkmcnt(8)
	s_barrier
	s_waitcnt lgkmcnt(0)
	s_setprio 0
	s_waitcnt lgkmcnt(0)
	v_mfma_f32_16x16x32_bf16 v[84:87], v[128:131], v[166:169], v[84:87]
	v_mfma_f32_16x16x32_bf16 v[76:79], v[148:151], v[166:169], v[76:79]
	v_mfma_f32_16x16x32_bf16 v[124:127], v[128:131], v[176:179], v[124:127]
	v_mfma_f32_16x16x32_bf16 v[72:75], v[148:151], v[176:179], v[72:75]
	v_mfma_f32_16x16x32_bf16 v[120:123], v[128:131], v[184:187], v[120:123]
	v_mfma_f32_16x16x32_bf16 v[96:99], v[148:151], v[184:187], v[96:99]
	v_mfma_f32_16x16x32_bf16 v[116:119], v[128:131], v[192:195], v[116:119]
	v_mfma_f32_16x16x32_bf16 v[92:95], v[148:151], v[192:195], v[92:95]
	v_mfma_f32_16x16x32_bf16 v[84:87], v[132:135], v[172:175], v[84:87]
	v_mfma_f32_16x16x32_bf16 v[76:79], v[162:165], v[172:175], v[76:79]
	v_mfma_f32_16x16x32_bf16 v[124:127], v[132:135], v[180:183], v[124:127]
	v_mfma_f32_16x16x32_bf16 v[72:75], v[162:165], v[180:183], v[72:75]
	v_mfma_f32_16x16x32_bf16 v[120:123], v[132:135], v[188:191], v[120:123]
	v_mfma_f32_16x16x32_bf16 v[96:99], v[162:165], v[188:191], v[96:99]
	v_mfma_f32_16x16x32_bf16 v[116:119], v[132:135], v[196:199], v[116:119]
	v_mfma_f32_16x16x32_bf16 v[92:95], v[162:165], v[196:199], v[92:95]
	s_setprio 1
	s_barrier
	s_add_i32 s12, s88, s78
	v_lshl_add_u64 v[216:217], s[70:71], 0, v[138:139]
	s_mov_b32 m0, s12
	ds_read_b128 v[200:203], v160
	ds_read_b128 v[204:207], v160 offset:1024
	ds_read_b128 v[208:211], v160 offset:2048
	ds_read_b128 v[212:215], v160 offset:3072
	global_load_lds_dwordx4 v[216:217], off
	v_lshl_add_u64 v[218:219], s[70:71], 0, v[142:143]
	s_add_i32 m0, s12, 0x2000
	s_nop 0
	global_load_lds_dwordx4 v[218:219], off
	s_barrier
; #define PG8_STAGE(bufoff, gbase, voff) do { _Pragma("unroll") for (int _i = 0; _i < 2; ++_i) \
;         __builtin_amdgcn_global_load_lds((const unsigned*)((const char*)(gbase) + (voff)[_i]), (LAS unsigned*)(lds + (bufoff) + ldsw + _i * 8192), 16, 0, 0); } while (0)
; #define PG8_LDA(dst, b, h) do { _Pragma("unroll") for (int m = 0; m < 4; ++m) _Pragma("unroll") for (int k = 0; k < 2; ++k) dst[m][k] = *(const LAS bf16x8*)(lds + PG8_SA(b, h) + aoff + m * 2048 + k * 1024); } while (0)
; #define PG8_LDB(dst, b, h) do { _Pragma("unroll") for (int n = 0; n < 2; ++n) _Pragma("unroll") for (int k = 0; k < 2; ++k) dst[n][k] = *(const LAS bf16x8*)(lds + PG8_SB(b, h) + boff + n * 2048 + k * 1024); } while (0)
; #define PG8_MMA(ai, bj, At, Bt) do { __builtin_amdgcn_s_setprio(1); _Pragma("unroll") for (int m = 0; m < 4; ++m) _Pragma("unroll") for (int n = 0; n < 2; ++n) _Pragma("unroll") for (int k = 0; k < 2; ++k) \
;         acc[ai][bj][m][n] = __builtin_amdgcn_mfma_f32_16x16x32_bf16(Bt[n][k], At[m][k], acc[ai][bj][m][n], 0, 0, 0); __builtin_amdgcn_s_setprio(0); } while (0)
; #define PG8_WAIT_V(n) asm volatile("s_waitcnt vmcnt(" #n ")" ::: "memory")
; #define PG8_WAIT_L(n) asm volatile("s_waitcnt lgkmcnt(" #n ")" ::: "memory")
; #define PG8_BAR __builtin_amdgcn_s_barrier()
; #define PG8_SCHED __builtin_amdgcn_sched_barrier(0)
; template <class Epi, class Sched>
; __device__ __forceinline__ void gemm_phase(LAS unsigned char* lds, const int K, const Sched& S, const Epi& E) {
;     ...
;             PG8_BAR; PG8_WAIT_L(0); PG8_MMA(0, 1, At, B1); PG8_BAR;
;             PG8_LDA(At, 0, 1); PG8_STAGE(PG8_SA(0, 0), a2, voffA);
;             PG8_BAR; PG8_WAIT_L(0); PG8_MMA(1, 0, At, B0); PG8_BAR; PG8_SCHED;
;             PG8_STAGE(PG8_SB(0, 1), b2 + hstep, voffB);
;             PG8_WAIT_V(6); PG8_BAR; PG8_MMA(1, 1, At, B1); PG8_BAR;
;             PG8_LDB(B0, 1, 0); PG8_SCHED; PG8_LDA(At, 1, 0); PG8_STAGE(PG8_SA(0, 1), a2 + hstepA, voffA);
;             PG8_WAIT_L(8); PG8_BAR; PG8_WAIT_L(0); PG8_MMA(0, 0, At, B0); PG8_BAR; PG8_SCHED;
;             PG8_LDB(B1, 1, 1); PG8_STAGE(PG8_SB(1, 0), b3, voffB);
	s_waitcnt lgkmcnt(0)
	s_setprio 0
	s_waitcnt lgkmcnt(0)
	v_mfma_f32_16x16x32_bf16 v[60:63], v[200:203], v[166:169], v[60:63]
	v_mfma_f32_16x16x32_bf16 v[16:19], v[208:211], v[166:169], v[16:19]
	v_mfma_f32_16x16x32_bf16 v[56:59], v[200:203], v[176:179], v[56:59]
	v_mfma_f32_16x16x32_bf16 v[12:15], v[208:211], v[176:179], v[12:15]
	v_mfma_f32_16x16x32_bf16 v[52:55], v[200:203], v[184:187], v[52:55]
	v_mfma_f32_16x16x32_bf16 v[28:31], v[208:211], v[184:187], v[28:31]
	v_mfma_f32_16x16x32_bf16 v[48:51], v[200:203], v[192:195], v[48:51]
	v_mfma_f32_16x16x32_bf16 v[24:27], v[208:211], v[192:195], v[24:27]
	v_mfma_f32_16x16x32_bf16 v[60:63], v[204:207], v[172:175], v[60:63]
	v_mfma_f32_16x16x32_bf16 v[16:19], v[212:215], v[172:175], v[16:19]
	v_mfma_f32_16x16x32_bf16 v[56:59], v[204:207], v[180:183], v[56:59]
	v_mfma_f32_16x16x32_bf16 v[12:15], v[212:215], v[180:183], v[12:15]
	v_mfma_f32_16x16x32_bf16 v[52:55], v[204:207], v[188:191], v[52:55]
	v_mfma_f32_16x16x32_bf16 v[28:31], v[212:215], v[188:191], v[28:31]
	v_mfma_f32_16x16x32_bf16 v[48:51], v[204:207], v[196:199], v[48:51]
	v_mfma_f32_16x16x32_bf16 v[24:27], v[212:215], v[196:199], v[24:27]
	s_setprio 1
	s_mov_b32 m0, s67
	v_lshl_add_u64 v[220:221], s[72:73], 0, v[136:137]
	s_barrier
	ds_read_b128 v[166:169], v159 offset:16384
	ds_read_b128 v[172:175], v159 offset:17408
	ds_read_b128 v[176:179], v159 offset:18432
	ds_read_b128 v[180:183], v159 offset:19456
	ds_read_b128 v[184:187], v159 offset:20480
	ds_read_b128 v[188:191], v159 offset:21504
	ds_read_b128 v[192:195], v159 offset:22528
	ds_read_b128 v[196:199], v159 offset:23552
	global_load_lds_dwordx4 v[220:221], off
	v_lshl_add_u64 v[222:223], s[72:73], 0, v[140:141]
	s_mov_b32 m0, s80
	s_nop 0
	global_load_lds_dwordx4 v[222:223], off
	s_barrier
	s_waitcnt lgkmcnt(0)
	s_setprio 0
	s_waitcnt lgkmcnt(0)
	v_mfma_f32_16x16x32_bf16 v[112:115], v[128:131], v[166:169], v[112:115]
	v_mfma_f32_16x16x32_bf16 v[88:91], v[148:151], v[166:169], v[88:91]
	v_mfma_f32_16x16x32_bf16 v[104:107], v[128:131], v[176:179], v[104:107]
	v_mfma_f32_16x16x32_bf16 v[80:83], v[148:151], v[176:179], v[80:83]
	v_mfma_f32_16x16x32_bf16 v[100:103], v[128:131], v[184:187], v[100:103]
	v_mfma_f32_16x16x32_bf16 v[64:67], v[148:151], v[184:187], v[64:67]
	v_mfma_f32_16x16x32_bf16 v[108:111], v[128:131], v[192:195], v[108:111]
	v_mfma_f32_16x16x32_bf16 v[68:71], v[148:151], v[192:195], v[68:71]
	v_mfma_f32_16x16x32_bf16 v[112:115], v[132:135], v[172:175], v[112:115]
	v_mfma_f32_16x16x32_bf16 v[88:91], v[162:165], v[172:175], v[88:91]
	v_mfma_f32_16x16x32_bf16 v[104:107], v[132:135], v[180:183], v[104:107]
	v_mfma_f32_16x16x32_bf16 v[80:83], v[162:165], v[180:183], v[80:83]
	v_mfma_f32_16x16x32_bf16 v[100:103], v[132:135], v[188:191], v[100:103]
	v_mfma_f32_16x16x32_bf16 v[64:67], v[162:165], v[188:191], v[64:67]
	v_mfma_f32_16x16x32_bf16 v[108:111], v[132:135], v[196:199], v[108:111]
	v_mfma_f32_16x16x32_bf16 v[68:71], v[162:165], v[196:199], v[68:71]
	s_setprio 1
	s_barrier
	s_add_u32 s12, s70, 0x40000
	s_addc_u32 s13, s71, 0
	s_add_i32 s52, s89, s78
	v_lshl_add_u64 v[128:129], s[12:13], 0, v[138:139]
	s_mov_b32 m0, s52
	s_nop 0
	global_load_lds_dwordx4 v[128:129], off
	v_lshl_add_u64 v[128:129], s[12:13], 0, v[142:143]
	s_add_i32 m0, s52, 0x2000
	s_nop 0
	global_load_lds_dwordx4 v[128:129], off
	s_waitcnt vmcnt(6)
	s_barrier
	s_setprio 0
	v_mfma_f32_16x16x32_bf16 v[44:47], v[200:203], v[166:169], v[44:47]
	v_mfma_f32_16x16x32_bf16 v[20:23], v[208:211], v[166:169], v[20:23]
	v_mfma_f32_16x16x32_bf16 v[40:43], v[200:203], v[176:179], v[40:43]
	v_mfma_f32_16x16x32_bf16 v[8:11], v[208:211], v[176:179], v[8:11]
	v_mfma_f32_16x16x32_bf16 v[36:39], v[200:203], v[184:187], v[36:39]
	v_mfma_f32_16x16x32_bf16 v[0:3], v[208:211], v[184:187], v[0:3]
	v_mfma_f32_16x16x32_bf16 v[32:35], v[200:203], v[192:195], v[32:35]
	v_mfma_f32_16x16x32_bf16 v[4:7], v[208:211], v[192:195], v[4:7]
	v_mfma_f32_16x16x32_bf16 v[44:47], v[204:207], v[172:175], v[44:47]
	v_mfma_f32_16x16x32_bf16 v[20:23], v[212:215], v[172:175], v[20:23]
	v_mfma_f32_16x16x32_bf16 v[40:43], v[204:207], v[180:183], v[40:43]
	v_mfma_f32_16x16x32_bf16 v[8:11], v[212:215], v[180:183], v[8:11]
	v_mfma_f32_16x16x32_bf16 v[36:39], v[204:207], v[188:191], v[36:39]
	v_mfma_f32_16x16x32_bf16 v[0:3], v[212:215], v[188:191], v[0:3]
	v_mfma_f32_16x16x32_bf16 v[32:35], v[204:207], v[196:199], v[32:35]
	v_mfma_f32_16x16x32_bf16 v[4:7], v[212:215], v[196:199], v[4:7]
	s_setprio 1
	s_add_i32 s52, 0, 0x18000
	v_add_u32_e32 v161, s52, v156
	s_barrier
	ds_read_b128 v[128:131], v161
	ds_read_b128 v[132:135], v161 offset:1024
	ds_read_b128 v[148:151], v161 offset:2048
	ds_read_b128 v[162:165], v161 offset:3072
	s_add_u32 s12, s72, 0x20000
	s_addc_u32 s13, s73, 0
	s_mov_b32 m0, s81
	v_lshl_add_u64 v[200:201], s[12:13], 0, v[136:137]
	ds_read_b128 v[166:169], v159 offset:32768
	ds_read_b128 v[172:175], v159 offset:33792
	ds_read_b128 v[176:179], v159 offset:34816
	ds_read_b128 v[180:183], v159 offset:35840
	ds_read_b128 v[184:187], v159 offset:36864
	ds_read_b128 v[188:191], v159 offset:37888
	ds_read_b128 v[192:195], v159 offset:38912
	ds_read_b128 v[196:199], v159 offset:39936
	global_load_lds_dwordx4 v[200:201], off
	v_lshl_add_u64 v[200:201], s[12:13], 0, v[140:141]
	s_mov_b32 m0, s82
	s_nop 0
	global_load_lds_dwordx4 v[200:201], off
	s_waitcnt lgkmcnt(8)
	s_barrier
; __device__ __forceinline__ unsigned cvt_pk_bf16(float lo, float hi) { unsigned r; asm volatile("v_cvt_pk_bf16_f32 %0, %1, %2" : "=v"(r) : "v"(lo), "v"(hi)); return r; }
; #define PG8_STAGE(bufoff, gbase, voff) do { _Pragma("unroll") for (int _i = 0; _i < 2; ++_i) \
;         __builtin_amdgcn_global_load_lds((const unsigned*)((const char*)(gbase) + (voff)[_i]), (LAS unsigned*)(lds + (bufoff) + ldsw + _i * 8192), 16, 0, 0); } while (0)
; template <class Epi, class Sched>
; __device__ __forceinline__ void gemm_phase(LAS unsigned char* lds, const int K, const Sched& S, const Epi& E) {
;     ...
;             PG8_WAIT_L(8); PG8_BAR; PG8_WAIT_L(0); PG8_MMA(0, 0, At, B0); PG8_BAR; PG8_SCHED;
;             PG8_LDB(B1, 1, 1); PG8_STAGE(PG8_SB(1, 0), b3, voffB);
;             PG8_BAR; PG8_WAIT_L(0); PG8_MMA(0, 1, At, B1); PG8_BAR;
;             PG8_LDA(At, 1, 1); PG8_STAGE(PG8_SA(1, 0), a3, voffA);
;             PG8_BAR; PG8_WAIT_L(0); PG8_MMA(1, 0, At, B0); PG8_BAR; PG8_SCHED;
;             PG8_STAGE(PG8_SB(1, 1), b3 + hstep, voffB);
;             PG8_WAIT_V(6); PG8_BAR; PG8_MMA(1, 1, At, B1); PG8_BAR;
;     __device__ __forceinline__ void operator()(f32x4 (&acc)[2][2][4][2], const Unit& u, int wr, int wc, int fr, int fq) const {
;         const int J0 = u.pn * 128 + wc * 32 + fq * 8, sc = u.pm * 2 + wr;
;         const bool f0 = (fr == 0), f15 = (fr == 15);
;         if (f0 || f15) {
; #pragma unroll
;             for (int bj = 0; bj < 2; ++bj)
; #pragma unroll
;                 for (int q = 0; q < 2; ++q) { const f32x4 a0 = f0 ? acc[0][bj][q][0] : acc[1][bj][2 + q][0], a1 = f0 ? acc[0][bj][q][1] : acc[1][bj][2 + q][1];
;                     u32x4 w; w.x = cvt_pk_bf16(a0[0], a0[1]); w.y = cvt_pk_bf16(a0[2], a0[3]); w.z = cvt_pk_bf16(a1[0], a1[1]); w.w = cvt_pk_bf16(a1[2], a1[3]);
;                     *(u32x4*)(side + (size_t)(sc * 4 + (f0 ? q : 2 + q)) * (2 * DFF) + bj * DFF + J0) = w; }
;         }
; #pragma unroll
;         for (int bj = 0; bj < 2; ++bj)
; #pragma unroll
;             for (int n = 0; n < 2; ++n) {
;                 const int col = bj * DFF + J0 + n * 4;
;                 const float csc = bj ? 0.6931471805599453f : 1.4426950408889634f;
;                 const f32x4 k0 = *(const f32x4*)(cw + col) * csc, k1 = *(const f32x4*)(cw + 2 * DFF + col) * csc, k2 = *(const f32x4*)(cw + 4 * DFF + col) * csc, kb = *(const f32x4*)(cb + col) * csc;
	s_waitcnt lgkmcnt(0)
	s_setprio 0
	s_waitcnt lgkmcnt(0)
	v_mfma_f32_16x16x32_bf16 v[84:87], v[128:131], v[166:169], v[84:87]
	v_mfma_f32_16x16x32_bf16 v[76:79], v[148:151], v[166:169], v[76:79]
	v_mfma_f32_16x16x32_bf16 v[124:127], v[128:131], v[176:179], v[124:127]
	v_mfma_f32_16x16x32_bf16 v[72:75], v[148:151], v[176:179], v[72:75]
	v_mfma_f32_16x16x32_bf16 v[120:123], v[128:131], v[184:187], v[120:123]
	v_mfma_f32_16x16x32_bf16 v[96:99], v[148:151], v[184:187], v[96:99]
	v_mfma_f32_16x16x32_bf16 v[116:119], v[128:131], v[192:195], v[116:119]
	v_mfma_f32_16x16x32_bf16 v[92:95], v[148:151], v[192:195], v[92:95]
	v_mfma_f32_16x16x32_bf16 v[84:87], v[132:135], v[172:175], v[84:87]
	v_mfma_f32_16x16x32_bf16 v[76:79], v[162:165], v[172:175], v[76:79]
	v_mfma_f32_16x16x32_bf16 v[124:127], v[132:135], v[180:183], v[124:127]
	v_mfma_f32_16x16x32_bf16 v[72:75], v[162:165], v[180:183], v[72:75]
	v_mfma_f32_16x16x32_bf16 v[120:123], v[132:135], v[188:191], v[120:123]
	v_mfma_f32_16x16x32_bf16 v[96:99], v[162:165], v[188:191], v[96:99]
	v_mfma_f32_16x16x32_bf16 v[116:119], v[132:135], v[196:199], v[116:119]
	v_mfma_f32_16x16x32_bf16 v[92:95], v[162:165], v[196:199], v[92:95]
	s_setprio 1
	s_barrier
	s_add_i32 s53, 0, 0x1c000
	s_add_i32 s12, s52, s78
	v_add_u32_e32 v161, s53, v156
	v_lshl_add_u64 v[216:217], v[216:217], 0, s[38:39]
	s_mov_b32 m0, s12
	ds_read_b128 v[200:203], v161
	ds_read_b128 v[204:207], v161 offset:1024
	ds_read_b128 v[208:211], v161 offset:2048
	ds_read_b128 v[212:215], v161 offset:3072
	global_load_lds_dwordx4 v[216:217], off
	v_lshl_add_u64 v[216:217], v[218:219], 0, s[38:39]
	s_add_i32 m0, s12, 0x2000
	s_nop 0
	global_load_lds_dwordx4 v[216:217], off
	s_barrier
	s_waitcnt lgkmcnt(0)
	s_setprio 0
	s_waitcnt lgkmcnt(0)
	v_mfma_f32_16x16x32_bf16 v[60:63], v[200:203], v[166:169], v[60:63]
	v_mfma_f32_16x16x32_bf16 v[16:19], v[208:211], v[166:169], v[16:19]
	v_mfma_f32_16x16x32_bf16 v[56:59], v[200:203], v[176:179], v[56:59]
	v_mfma_f32_16x16x32_bf16 v[12:15], v[208:211], v[176:179], v[12:15]
	v_mfma_f32_16x16x32_bf16 v[52:55], v[200:203], v[184:187], v[52:55]
	v_mfma_f32_16x16x32_bf16 v[28:31], v[208:211], v[184:187], v[28:31]
	v_mfma_f32_16x16x32_bf16 v[48:51], v[200:203], v[192:195], v[48:51]
	v_mfma_f32_16x16x32_bf16 v[24:27], v[208:211], v[192:195], v[24:27]
	v_mfma_f32_16x16x32_bf16 v[60:63], v[204:207], v[172:175], v[60:63]
	v_mfma_f32_16x16x32_bf16 v[16:19], v[212:215], v[172:175], v[16:19]
	v_mfma_f32_16x16x32_bf16 v[56:59], v[204:207], v[180:183], v[56:59]
	v_mfma_f32_16x16x32_bf16 v[12:15], v[212:215], v[180:183], v[12:15]
	v_mfma_f32_16x16x32_bf16 v[52:55], v[204:207], v[188:191], v[52:55]
	v_mfma_f32_16x16x32_bf16 v[28:31], v[212:215], v[188:191], v[28:31]
	v_mfma_f32_16x16x32_bf16 v[48:51], v[204:207], v[196:199], v[48:51]
	v_mfma_f32_16x16x32_bf16 v[24:27], v[212:215], v[196:199], v[24:27]
	s_setprio 1
	s_mov_b32 m0, s84
	v_lshl_add_u64 v[216:217], v[220:221], 0, s[38:39]
	s_barrier
	ds_read_b128 v[166:169], v159 offset:49152
	ds_read_b128 v[172:175], v159 offset:50176
	ds_read_b128 v[176:179], v159 offset:51200
	ds_read_b128 v[180:183], v159 offset:52224
	ds_read_b128 v[184:187], v159 offset:53248
	ds_read_b128 v[188:191], v159 offset:54272
	ds_read_b128 v[192:195], v159 offset:55296
	ds_read_b128 v[196:199], v159 offset:56320
	global_load_lds_dwordx4 v[216:217], off
	v_lshl_add_u64 v[216:217], v[222:223], 0, s[38:39]
	s_mov_b32 m0, s85
	s_nop 0
	global_load_lds_dwordx4 v[216:217], off
	s_barrier
	s_waitcnt lgkmcnt(0)
	s_setprio 0
	s_waitcnt lgkmcnt(0)
	v_mfma_f32_16x16x32_bf16 v[112:115], v[128:131], v[166:169], v[112:115]
	v_mfma_f32_16x16x32_bf16 v[88:91], v[148:151], v[166:169], v[88:91]
	v_mfma_f32_16x16x32_bf16 v[104:107], v[128:131], v[176:179], v[104:107]
	v_mfma_f32_16x16x32_bf16 v[80:83], v[148:151], v[176:179], v[80:83]
	v_mfma_f32_16x16x32_bf16 v[100:103], v[128:131], v[184:187], v[100:103]
	v_mfma_f32_16x16x32_bf16 v[64:67], v[148:151], v[184:187], v[64:67]
	v_mfma_f32_16x16x32_bf16 v[108:111], v[128:131], v[192:195], v[108:111]
	v_mfma_f32_16x16x32_bf16 v[68:71], v[148:151], v[192:195], v[68:71]
	v_mfma_f32_16x16x32_bf16 v[112:115], v[132:135], v[172:175], v[112:115]
	v_mfma_f32_16x16x32_bf16 v[88:91], v[162:165], v[172:175], v[88:91]
	v_mfma_f32_16x16x32_bf16 v[104:107], v[132:135], v[180:183], v[104:107]
	v_mfma_f32_16x16x32_bf16 v[80:83], v[162:165], v[180:183], v[80:83]
	v_mfma_f32_16x16x32_bf16 v[100:103], v[132:135], v[188:191], v[100:103]
	v_mfma_f32_16x16x32_bf16 v[64:67], v[162:165], v[188:191], v[64:67]
	v_mfma_f32_16x16x32_bf16 v[108:111], v[132:135], v[196:199], v[108:111]
	v_mfma_f32_16x16x32_bf16 v[68:71], v[162:165], v[196:199], v[68:71]
	s_setprio 1
	s_barrier
	s_add_u32 s12, s70, 0x40080
	s_addc_u32 s13, s71, 0
	s_add_i32 s52, s53, s78
	v_lshl_add_u64 v[128:129], s[12:13], 0, v[138:139]
	s_mov_b32 m0, s52
	s_nop 0
	global_load_lds_dwordx4 v[128:129], off
	v_lshl_add_u64 v[128:129], s[12:13], 0, v[142:143]
	s_add_i32 m0, s52, 0x2000
	s_nop 0
	global_load_lds_dwordx4 v[128:129], off
	s_waitcnt vmcnt(6)
	s_barrier
	s_setprio 0
	v_mfma_f32_16x16x32_bf16 v[44:47], v[200:203], v[166:169], v[44:47]
	v_mfma_f32_16x16x32_bf16 v[20:23], v[208:211], v[166:169], v[20:23]
	v_mfma_f32_16x16x32_bf16 v[40:43], v[200:203], v[176:179], v[40:43]
	v_mfma_f32_16x16x32_bf16 v[8:11], v[208:211], v[176:179], v[8:11]
	v_mfma_f32_16x16x32_bf16 v[36:39], v[200:203], v[184:187], v[36:39]
	v_mfma_f32_16x16x32_bf16 v[0:3], v[208:211], v[184:187], v[0:3]
	v_mfma_f32_16x16x32_bf16 v[32:35], v[200:203], v[192:195], v[32:35]
	v_mfma_f32_16x16x32_bf16 v[4:7], v[208:211], v[192:195], v[4:7]
	v_mfma_f32_16x16x32_bf16 v[44:47], v[204:207], v[172:175], v[44:47]
	v_mfma_f32_16x16x32_bf16 v[20:23], v[212:215], v[172:175], v[20:23]
	v_mfma_f32_16x16x32_bf16 v[40:43], v[204:207], v[180:183], v[40:43]
	v_mfma_f32_16x16x32_bf16 v[8:11], v[212:215], v[180:183], v[8:11]
	v_mfma_f32_16x16x32_bf16 v[36:39], v[204:207], v[188:191], v[36:39]
	v_mfma_f32_16x16x32_bf16 v[0:3], v[212:215], v[188:191], v[0:3]
	v_mfma_f32_16x16x32_bf16 v[32:35], v[204:207], v[196:199], v[32:35]
	v_mfma_f32_16x16x32_bf16 v[4:7], v[212:215], v[196:199], v[4:7]
	s_setprio 1
	s_add_i32 s49, s49, 2
	s_add_u32 s11, s11, 0x100
	s_addc_u32 s33, s33, 0
	s_cmp_gt_u32 s49, 13
	s_mov_b64 s[12:13], s[68:69]
	s_barrier
	s_cbranch_scc0 .LBB0_800
	s_setprio 0
	v_lshl_or_b32 v150, s10, 7, v157
	v_add_u32_e32 v254, 0x2c00, v253
	global_load_dwordx4 v[208:211], v253, s[22:23] offset:16
	global_load_dwordx4 v[212:215], v253, s[24:25] offset:16
	global_load_dwordx4 v[216:219], v253, s[26:27] offset:16
	global_load_dwordx4 v[220:223], v253, s[36:37] offset:16
	v_cmp_gt_i32_e32 vcc, 15, v152
	s_mov_b64 s[70:71], -1
	s_and_saveexec_b64 s[68:69], vcc
	s_cbranch_execz .LBB0_805
	v_cmp_eq_u32_e32 vcc, 0, v152
	v_cmp_ne_u32_e64 s[12:13], 0, v152
	s_and_saveexec_b64 s[70:71], s[12:13]
	v_ashrrev_i32_e32 v151, 31, v150
	v_mov_b64_e32 v[148:149], v[150:151]
	s_or_b64 exec, exec, s[70:71]
	s_orn2_b64 s[70:71], vcc, exec
